# grid-barrier seams: non-leader L1 invalidate issued at arrival (before polling) instead of after release
# speedup vs baseline: 1.0080x; 1.0080x over previous
.LBB0_129:
	s_or_b64 exec, exec, s[8:9]
	v_cvt_f32_u32_e32 v4, v2
	s_waitcnt vmcnt(0)
	v_readfirstlane_b32 s6, v3
	v_sub_u32_e32 v3, 0, v2
	v_rcp_iflag_f32_e32 v4, v4
	v_add_u32_e32 v5, s6, v1
	v_mul_f32_e32 v4, 0x4f7ffffe, v4
	v_cvt_u32_f32_e32 v4, v4
	v_mul_lo_u32 v1, v3, v4
	v_mul_hi_u32 v1, v4, v1
	v_add_u32_e32 v1, v4, v1
	v_mul_hi_u32 v1, v5, v1
	v_mul_lo_u32 v3, v1, v2
	v_sub_u32_e32 v3, v5, v3
	v_add_u32_e32 v4, 1, v1
	v_cmp_ge_u32_e32 vcc, v3, v2
	s_nop 1
	v_cndmask_b32_e32 v1, v1, v4, vcc
	v_sub_u32_e32 v4, v3, v2
	v_cndmask_b32_e32 v3, v3, v4, vcc
	v_add_u32_e32 v4, 1, v1
	v_cmp_ge_u32_e32 vcc, v3, v2
	v_add_u32_e32 v3, 1, v5
	s_nop 0
	v_cndmask_b32_e32 v1, v1, v4, vcc
	v_mul_lo_u32 v4, v2, v1
	v_add_u32_e32 v2, v4, v2
	v_cmp_ne_u32_e32 vcc, v3, v2
	s_and_saveexec_b64 s[6:7], vcc
	s_xor_b64 s[6:7], exec, s[6:7]
	s_cbranch_execz .LBB0_143
	buffer_inv sc1
	s_waitcnt lgkmcnt(0)
	v_mov_b32_e32 v0, 0x2000
	global_load_dword v0, v0, s[4:5] offset:1024 sc1
	s_add_u32 s12, s4, 0x2400
	s_addc_u32 s13, s5, 0
	s_waitcnt vmcnt(0)
	v_cmp_eq_u32_e32 vcc, v0, v1
	s_and_saveexec_b64 s[8:9], vcc
	s_cbranch_execz .LBB0_142
	s_add_u32 s10, s2, 0x4200
	s_addc_u32 s11, s3, 0
	s_mov_b32 s24, 1
	s_mov_b64 s[14:15], 0
	v_mov_b32_e32 v0, 0
	s_branch .LBB0_133

.LBB0_142:
	s_or_b64 exec, exec, s[8:9]
	s_waitcnt vmcnt(0)
	s_waitcnt vmcnt(0)

.LBB0_268:
	s_or_b64 exec, exec, s[10:11]
	v_cvt_f32_u32_e32 v5, v3
	s_waitcnt vmcnt(0)
	v_readfirstlane_b32 s8, v4
	v_sub_u32_e32 v4, 0, v3
	v_rcp_iflag_f32_e32 v5, v5
	v_add_u32_e32 v6, s8, v2
	v_mul_f32_e32 v5, 0x4f7ffffe, v5
	v_cvt_u32_f32_e32 v5, v5
	v_mul_lo_u32 v2, v4, v5
	v_mul_hi_u32 v2, v5, v2
	v_add_u32_e32 v2, v5, v2
	v_mul_hi_u32 v2, v6, v2
	v_mul_lo_u32 v4, v2, v3
	v_sub_u32_e32 v4, v6, v4
	v_add_u32_e32 v5, 1, v2
	v_cmp_ge_u32_e32 vcc, v4, v3
	s_nop 1
	v_cndmask_b32_e32 v2, v2, v5, vcc
	v_sub_u32_e32 v5, v4, v3
	v_cndmask_b32_e32 v4, v4, v5, vcc
	v_add_u32_e32 v5, 1, v2
	v_cmp_ge_u32_e32 vcc, v4, v3
	v_add_u32_e32 v4, 1, v6
	s_nop 0
	v_cndmask_b32_e32 v2, v2, v5, vcc
	v_mul_lo_u32 v5, v3, v2
	v_add_u32_e32 v3, v5, v3
	v_cmp_ne_u32_e32 vcc, v4, v3
	s_and_saveexec_b64 s[8:9], vcc
	s_xor_b64 s[8:9], exec, s[8:9]
	s_cbranch_execz .LBB0_282
	buffer_inv sc1
	s_waitcnt lgkmcnt(0)
	global_load_dword v0, v252, s[4:5] offset:1024 sc1
	s_add_u32 s14, s4, 0x2400
	s_addc_u32 s15, s5, 0
	s_waitcnt vmcnt(0)
	v_cmp_eq_u32_e32 vcc, v0, v2
	s_and_saveexec_b64 s[10:11], vcc
	s_cbranch_execz .LBB0_281
	s_add_u32 s12, s2, 0x4200
	s_addc_u32 s13, s3, 0
	s_mov_b32 s26, 1
	s_mov_b64 s[16:17], 0
	s_branch .LBB0_272

.LBB0_281:
	s_or_b64 exec, exec, s[10:11]
	s_waitcnt vmcnt(0)
	s_waitcnt vmcnt(0)

.LBB0_545:
	s_or_b64 exec, exec, s[8:9]
	v_cvt_f32_u32_e32 v5, v3
	s_waitcnt vmcnt(0)
	v_readfirstlane_b32 s6, v4
	v_sub_u32_e32 v4, 0, v3
	v_rcp_iflag_f32_e32 v5, v5
	v_add_u32_e32 v6, s6, v2
	v_mul_f32_e32 v5, 0x4f7ffffe, v5
	v_cvt_u32_f32_e32 v5, v5
	v_mul_lo_u32 v2, v4, v5
	v_mul_hi_u32 v2, v5, v2
	v_add_u32_e32 v2, v5, v2
	v_mul_hi_u32 v2, v6, v2
	v_mul_lo_u32 v4, v2, v3
	v_sub_u32_e32 v4, v6, v4
	v_add_u32_e32 v5, 1, v2
	v_cmp_ge_u32_e32 vcc, v4, v3
	s_nop 1
	v_cndmask_b32_e32 v2, v2, v5, vcc
	v_sub_u32_e32 v5, v4, v3
	v_cndmask_b32_e32 v4, v4, v5, vcc
	v_add_u32_e32 v5, 1, v2
	v_cmp_ge_u32_e32 vcc, v4, v3
	v_add_u32_e32 v4, 1, v6
	s_nop 0
	v_cndmask_b32_e32 v2, v2, v5, vcc
	v_mul_lo_u32 v5, v3, v2
	v_add_u32_e32 v3, v5, v3
	v_cmp_ne_u32_e32 vcc, v4, v3
	s_and_saveexec_b64 s[6:7], vcc
	s_xor_b64 s[6:7], exec, s[6:7]
	s_cbranch_execz .LBB0_559
	buffer_inv sc1
	s_waitcnt lgkmcnt(0)
	global_load_dword v0, v252, s[4:5] offset:1024 sc1
	s_add_u32 s12, s4, 0x2400
	s_addc_u32 s13, s5, 0
	s_waitcnt vmcnt(0)
	v_cmp_eq_u32_e32 vcc, v0, v2
	s_and_saveexec_b64 s[8:9], vcc
	s_cbranch_execz .LBB0_558
	s_add_u32 s10, s2, 0x4200
	s_addc_u32 s11, s3, 0
	s_mov_b32 s24, 1
	s_mov_b64 s[14:15], 0
	s_branch .LBB0_549
